# dry-queue bitmask now read with returning atomic add 0 (same coherence path as the pops) instead of sc1 loads; otherwise identical to the dry-queue batch-skip build
# speedup vs baseline: 1.0080x; 1.0002x over previous
; __global__ void __launch_bounds__(NTHR, 2) fwd_kernel(Ptrs P) {
;     ...
; #pragma unroll 1
;         for (int qx = 0; qx < 8; ++qx) {
;             const int xq = (xcc + qx) & 7;
;             const int h0 = xq, h1 = 7 - xq, h2 = (xq + 4) & 7, h3 = 7 - h2;
;             const int r0 = (h1 > h0) + (h2 > h0) + (h3 > h0), r1 = (h0 > h1) + (h2 > h1) + (h3 > h1), r2 = (h0 > h2) + (h1 > h2) + (h3 > h2);
; #pragma unroll 1
;             for (;;) {
;                 if (tid == 0) *qslot = (int)atomicAdd((unsigned*)(ws + 256 + 256 * xq), 1u);
;                 __syncthreads();
;                 const int idx = *qslot;
;                 __syncthreads();
;                 if (idx >= 128) break;
;                 const int k = idx >> 5, qblk = 31 - (idx & 31);
.LBB0_381:
	s_cmp_eq_u32 s51, 7
	s_cbranch_scc1 .LBB0_424
	s_and_saveexec_b64 s[2:3], s[8:9]
	s_cbranch_execz .La_qs_bcast
	v_mov_b32_e32 v10, 0
	global_atomic_add v2, v1, v10, s[68:69] offset:256 sc0
	global_atomic_add v3, v1, v10, s[68:69] offset:512 sc0
	global_atomic_add v4, v1, v10, s[68:69] offset:768 sc0
	global_atomic_add v5, v1, v10, s[68:69] offset:1024 sc0
	global_atomic_add v6, v1, v10, s[68:69] offset:1280 sc0
	global_atomic_add v7, v1, v10, s[68:69] offset:1536 sc0
	global_atomic_add v8, v1, v10, s[68:69] offset:1792 sc0
	global_atomic_add v9, v1, v10, s[68:69] offset:2048 sc0
	s_waitcnt vmcnt(0)
	v_lshrrev_b32_e32 v2, 7, v2
	v_min_u32_e32 v2, 1, v2
	v_lshl_or_b32 v10, v2, 0, v10
	v_lshrrev_b32_e32 v3, 7, v3
	v_min_u32_e32 v3, 1, v3
	v_lshl_or_b32 v10, v3, 1, v10
	v_lshrrev_b32_e32 v4, 7, v4
	v_min_u32_e32 v4, 1, v4
	v_lshl_or_b32 v10, v4, 2, v10
	v_lshrrev_b32_e32 v5, 7, v5
	v_min_u32_e32 v5, 1, v5
	v_lshl_or_b32 v10, v5, 3, v10
	v_lshrrev_b32_e32 v6, 7, v6
	v_min_u32_e32 v6, 1, v6
	v_lshl_or_b32 v10, v6, 4, v10
	v_lshrrev_b32_e32 v7, 7, v7
	v_min_u32_e32 v7, 1, v7
	v_lshl_or_b32 v10, v7, 5, v10
	v_lshrrev_b32_e32 v8, 7, v8
	v_min_u32_e32 v8, 1, v8
	v_lshl_or_b32 v10, v8, 6, v10
	v_lshrrev_b32_e32 v9, 7, v9
	v_min_u32_e32 v9, 1, v9
	v_lshl_or_b32 v10, v9, 7, v10
	v_mov_b32_e32 v11, s50
	ds_write_b32 v11, v10
